# diff-attention tile: overflow guard of the lazy softmax reference taken from the row partial sum instead of a 20-op max tree; exps written to spare registers so the rare path keeps the scores
# speedup vs baseline: 1.0091x; 1.0008x over previous
; #define LAS __attribute__((address_space(3)))
; template <int MODE>
; __device__ __forceinline__ void attn_unit(LAS char* lds, const AttnPtrs& A, int b, int qb) {
;     ...
;     const int tid = opaque_tid(), lane = tid & 63, r32 = lane & 31, hi = lane >> 5, wid = __builtin_amdgcn_readfirstlane(tid >> 6);
;     const int strm = (MODE == 2) ? (wid & 1) : 0;
;     const size_t rowbase = (size_t)b * SEQ; const int q0 = (MODE == 2) ? qb * 128 + (wid >> 1) * 32 : qb * 256 + wid * 32; const int cw = q0 >> 6, NT = (MODE == 2) ? 2 * qb + 2 : 4 * qb + 4;
;     const size_t qrow = rowbase + q0 + r32;
;     const bf16_t* ksrc[2]; const bf16_t* vsrc[2];
; #pragma unroll
;     for (int i = 0; i < 2; ++i) { const unsigned row = 4u * (2 * wid + i) + (lane >> 4), ch = (lane & 15) ^ (((row & 3) << 2) | ((row >> 2) & 3));
;         ksrc[i] = A.K + (rowbase + row) * A.ldk + ch * 8; vsrc[i] = A.V + (rowbase + row) * A.ldv + ch * 8; }
;     const bf16_t* k64src = nullptr;
;     if constexpr (MODE == 0) { const unsigned row = 8u * wid + (lane >> 3), ch = (lane & 7) ^ ((row >> 1) & 7); k64src = A.K64 + (rowbase + row) * 64 + ch * 8; }
;     const unsigned fK = ((r32 & 3) << 2) | ((r32 >> 2) & 3);
;     const unsigned g64 = (r32 >> 1) & 7;
;     const int q4 = (lane & 15) >> 2, p4 = lane & 3, blk = (lane >> 4) & 1;
;     unsigned vrow[2], vlow[2];
; #pragma unroll
;     for (int t = 0; t < 2; ++t) { vrow[t] = 4 * hi + 8 * t + q4; vlow[t] = (unsigned)((2 * blk + (p4 >> 1)) ^ ((hi + 2 * t) & 3)); }
;     ...
;     STAGE(0, 0); STAGE(1, 1);
;     bf16x8 qf[NQ];
; #pragma unroll
;     for (int s = 0; s < NQ; ++s) qf[s] = *(const bf16x8*)(A.Q + qrow * A.ldq + 64 * strm + 16 * s + 8 * hi);
;     ...
;               for (int it = bx;;) {
;                 if (it >= 640) break;
;                 const int qb = 31 - it / 20, bh = it % 20, b = bh / 5, h = bh % 5;
;                 att::AttnPtrs A{QKC + 2 * h * 64, 1280, QKC + 640 + 2 * h * 64, 1280, nullptr, VBC + 640 + h * 128, 1280, GATE + 1408 + h * 128, GATE + 1408 + h * 128, nullptr, lam, 1.0f - lam_init, ap->subln_g + L * 128};
;     ...
;                 att::attn_unit<2>((LAS char*)lds, A, b, qb);
.LBB0_623:
	s_mul_hi_i32 s3, s2, 0x99999999
	s_lshr_b32 s4, s3, 31
	s_ashr_i32 s3, s3, 3
	s_add_i32 s3, s3, s4
	s_mul_hi_i32 s4, s2, 0x66666667
	s_lshr_b32 s5, s4, 31
	s_lshr_b32 s4, s4, 3
	s_add_i32 s4, s4, s5
	s_mul_i32 s4, s4, 20
	s_sub_i32 s4, s2, s4
	s_bfe_i32 s2, s4, 0x80000
	s_mulk_i32 s2, 0x67
	s_sext_i32_i16 s5, s2
	s_ashr_i32 s5, s5, 9
	s_bfe_u32 s2, s2, 0x1000f
	s_add_i32 s2, s5, s2
	s_mul_i32 s5, s2, 5
	s_sub_i32 s4, s4, s5
	s_sext_i32_i8 s4, s4
	s_lshl_b32 s4, s4, 7
	s_ashr_i32 s5, s4, 31
	s_add_i32 s24, s3, 31
	s_lshl_b64 s[4:5], s[4:5], 1
	s_add_u32 s6, s10, s4
	s_addc_u32 s7, s11, s5
	s_add_u32 s28, s12, s4
	s_addc_u32 s29, s13, s5
	s_add_u32 s34, s18, s4
	s_getreg_b32 s8, hwreg(HW_REG_HW_ID, 0, 6)
	s_addc_u32 s35, s19, s5
	s_lshl_b32 s8, s8, 2
	s_and_b32 s8, s8, 0xfc
	s_add_i32 s8, s8, 0x20040
	v_mov_b32_e32 v0, s8
	ds_read_b32 v0, v0
	s_lshl_b32 s25, s24, 7
	v_mov_b64_e32 v[8:9], s[28:29]
	v_mov_b64_e32 v[12:13], s[34:35]
	s_lshl_b32 s24, s24, 1
	s_waitcnt lgkmcnt(0)
	v_readfirstlane_b32 s8, v0
	v_mov_b32_e32 v0, v1
	v_mov_b32_e32 v3, v1
	v_mbcnt_lo_u32_b32 v0, -1, v0
	v_mbcnt_hi_u32_b32 v6, -1, v0
	v_lshl_or_b32 v0, s8, 6, v6
	s_bfe_i64 s[8:9], s[2:3], 0x100000
	v_readfirstlane_b32 s23, v0
	s_ashr_i32 s26, s23, 6
	s_ashr_i32 s23, s23, 7
	s_lshl_b32 s27, s23, 5
	s_add_i32 s27, s27, s25
	s_lshl_b32 s25, s26, 3
	v_bfe_u32 v16, v6, 4, 2
	s_lshl_b64 s[8:9], s[8:9], 12
	v_or_b32_e32 v0, s25, v16
	v_lshl_add_u64 v[4:5], s[8:9], 0, v[0:1]
	s_lshl_b32 s44, s26, 1
	v_mad_u64_u32 v[10:11], s[28:29], v4, s84, v[8:9]
	v_mad_u64_u32 v[14:15], s[28:29], v4, s84, v[12:13]
	s_or_b32 s25, s25, 4
	v_and_b32_e32 v17, 15, v6
	v_lshlrev_b32_e32 v18, 2, v16
	s_and_b32 s44, s44, 2
	v_mad_i32_i24 v11, v5, s84, v11
	v_mad_i32_i24 v15, v5, s84, v15
	v_or_b32_e32 v4, s25, v16
	s_bfe_u32 s25, s25, 0x20002
	v_mov_b32_e32 v5, v1
	s_ashr_i32 s33, s27, 31
	v_bitop3_b32 v2, s44, v17, v18 bitop3:0x36
	v_bitop3_b32 v18, s25, v17, v18 bitop3:0x36
	v_lshl_add_u64 v[16:17], s[8:9], 0, v[4:5]
	s_ashr_i32 s25, s27, 6
	v_mad_u64_u32 v[8:9], s[28:29], v16, s84, v[8:9]
	v_mad_u64_u32 v[12:13], s[28:29], v16, s84, v[12:13]
	s_add_u32 s27, s8, s27
	s_addc_u32 s28, s9, s33
	s_lshl_b32 s9, s26, 11
	v_lshlrev_b32_e32 v2, 4, v2
	s_add_i32 s9, s9, 0
	v_lshl_add_u64 v[10:11], v[10:11], 0, v[2:3]
	v_mad_i32_i24 v9, v17, s84, v9
	v_lshlrev_b32_e32 v4, 4, v18
	s_mov_b32 m0, s9
	v_lshl_add_u64 v[8:9], v[8:9], 0, v[4:5]
	global_load_lds_dwordx4 v[10:11], off
	s_add_i32 m0, s9, 0x400
	v_lshl_add_u64 v[14:15], v[14:15], 0, v[2:3]
	v_mad_i32_i24 v13, v17, s84, v13
	global_load_lds_dwordx4 v[8:9], off
	s_add_i32 m0, s9, 0x4000
	v_lshl_add_u64 v[12:13], v[12:13], 0, v[4:5]
	global_load_lds_dwordx4 v[14:15], off
	s_add_i32 m0, s9, 0x4400
	v_lshl_add_u64 v[10:11], v[10:11], 0, s[60:61]
	global_load_lds_dwordx4 v[12:13], off
	s_add_i32 m0, s9, 0xa000
	v_lshl_add_u64 v[8:9], v[8:9], 0, s[60:61]
	global_load_lds_dwordx4 v[10:11], off
	s_add_i32 m0, s9, 0xa400
	v_and_b32_e32 v7, 31, v6
	global_load_lds_dwordx4 v[8:9], off
	v_lshl_add_u64 v[8:9], v[14:15], 0, s[60:61]
	s_add_i32 m0, s9, 0xe000
	v_or_b32_e32 v114, s27, v7
	global_load_lds_dwordx4 v[8:9], off
	v_lshl_add_u64 v[8:9], v[12:13], 0, s[60:61]
	s_add_i32 m0, s9, 0xe400
	s_and_b32 s8, s26, 1
	global_load_lds_dwordx4 v[8:9], off
	v_mov_b64_e32 v[8:9], s[6:7]
	v_mad_u64_u32 v[8:9], s[6:7], v114, s84, v[8:9]
	v_mov_b32_e32 v10, 0xa00
	v_bfe_u32 v16, v6, 5, 1
	v_mad_i32_i24 v9, s28, v10, v9
	s_lshl_b32 s68, s8, 7
	v_lshl_add_u64 v[8:9], v[8:9], 0, s[68:69]
	v_lshlrev_b32_e32 v10, 4, v16
	v_mov_b32_e32 v11, v1
	v_lshl_add_u64 v[8:9], v[8:9], 0, v[10:11]
	global_load_dwordx4 v[98:101], v[8:9], off
	global_load_dwordx4 v[102:105], v[8:9], off offset:32
	global_load_dwordx4 v[106:109], v[8:9], off offset:64
	global_load_dwordx4 v[110:113], v[8:9], off offset:96
	v_lshlrev_b32_e32 v17, 2, v6
	v_bfe_u32 v18, v6, 2, 2
	v_and_or_b32 v8, v17, 12, v18
	s_lshl_b32 s6, s8, 3
	v_lshlrev_b32_e32 v9, 3, v6
	v_mov_b32_e32 v10, 0x4000
	v_lshrrev_b32_e32 v19, 3, v6
	v_lshlrev_b32_e32 v124, 8, v7
	v_or_b32_e32 v7, s6, v16
	v_and_or_b32 v125, v9, 8, v10
	v_bitop3_b32 v9, s6, v8, v16 bitop3:0x36
	v_and_b32_e32 v19, 2, v19
	v_bfe_u32 v20, v6, 1, 1
	v_lshlrev_b32_e32 v126, 4, v9
	v_bitop3_b32 v9, v7, v8, 2 bitop3:0x36
	v_or_b32_e32 v21, v19, v20
	v_lshlrev_b32_e32 v127, 4, v9
	v_bitop3_b32 v9, v7, v8, 4 bitop3:0x36
	v_bitop3_b32 v7, v7, v8, 6 bitop3:0x36
	v_bitop3_b32 v19, v19, v16, v20 bitop3:0x36
	v_bitop3_b32 v23, v16, v21, 2 bitop3:0x36
	v_lshlrev_b32_e32 v129, 4, v7
	v_and_b32_e32 v7, 12, v6
	v_or_b32_e32 v8, v19, v7
	v_or_b32_e32 v7, v23, v7
	v_or_b32_e32 v20, 2, v16
	v_lshlrev_b32_e32 v133, 4, v7
	v_bitop3_b32 v7, v6, 4, 12 bitop3:0x6c
	v_lshlrev_b32_e32 v131, 4, v8
	v_bitop3_b32 v8, v21, v7, v16 bitop3:0xde
	v_bitop3_b32 v7, v20, v7, v21 bitop3:0xde
	v_lshlrev_b32_e32 v141, 4, v7
	v_bitop3_b32 v7, v6, 8, 12 bitop3:0x6c
	v_and_b32_e32 v123, 63, v6
	v_lshlrev_b32_e32 v140, 4, v8
	v_bitop3_b32 v8, v21, v7, v16 bitop3:0xde
	v_bitop3_b32 v7, v20, v7, v21 bitop3:0xde
	v_bitop3_b32 v6, v6, 12, v6 bitop3:0xc
	v_lshlrev_b32_e32 v143, 4, v7
	v_bitop3_b32 v7, v21, v6, v16 bitop3:0xde
	v_bitop3_b32 v6, v20, v6, v21 bitop3:0xde
	v_lshlrev_b32_e32 v145, 4, v6
	v_or_b32_e32 v6, 4, v0
	v_lshlrev_b32_e32 v144, 4, v7
	v_mad_u64_u32 v[6:7], s[6:7], v6, s84, 0
	s_sext_i32_i16 s2, s2
	v_mad_i64_i32 v[6:7], s[6:7], s2, v214, v[6:7]
	v_lshl_add_u64 v[4:5], v[6:7], 0, v[4:5]
	v_lshl_add_u64 v[116:117], s[14:15], 0, v[4:5]
	v_mad_u64_u32 v[4:5], s[6:7], v0, s84, 0
	v_lshlrev_b32_e32 v122, 2, v16
	v_mad_i64_i32 v[4:5], s[6:7], s2, v214, v[4:5]
	v_or_b32_e32 v22, v122, v18
	v_lshl_add_u64 v[2:3], v[4:5], 0, v[2:3]
	v_mov_b32_e32 v14, v1
	v_mov_b32_e32 v15, v1
	s_waitcnt vmcnt(0)
	s_waitcnt vmcnt(0) lgkmcnt(0)
	s_barrier
; template <int MODE>
; __device__ __forceinline__ void attn_unit(LAS char* lds, const AttnPtrs& A, int b, int qb) {
;     ...
;     f32x16 o1[4];
; #pragma unroll
;     for (int c = 0; c < 4; ++c) o1[c] = f32x16{};
;     float m1 = -1e30f, l1 = 0.f;
;     unsigned long long mw_next = 0ull;
;     if constexpr (MODE == 1) { mw_next = A.MASK[qrow * 64]; asm volatile("" : "+v"(mw_next)); }
;     bf16x8 pk[4]; float a1 = 1.f;
	v_lshlrev_b32_e32 v128, 4, v9
	v_lshlrev_b32_e32 v130, 8, v22
	v_lshlrev_b32_e32 v142, 4, v8
	v_lshl_add_u64 v[118:119], s[14:15], 0, v[2:3]
	v_mov_b32_e32 v0, v1
	v_mov_b32_e32 v2, v1
	v_mov_b32_e32 v3, v1
	v_mov_b32_e32 v4, v1
	v_mov_b32_e32 v5, v1
	v_mov_b32_e32 v6, v1
	v_mov_b32_e32 v7, v1
	v_mov_b32_e32 v8, v1
	v_mov_b32_e32 v9, v1
	v_mov_b32_e32 v10, v1
	v_mov_b32_e32 v12, v1
	v_mov_b32_e32 v13, v1
	v_mov_b64_e32 v[64:65], v[14:15]
	v_mov_b64_e32 v[48:49], v[14:15]
	v_mov_b64_e32 v[32:33], v[14:15]
	s_lshl_b32 s6, s3, 1
	v_mov_b64_e32 v[62:63], v[12:13]
	v_mov_b64_e32 v[60:61], v[10:11]
	v_mov_b64_e32 v[58:59], v[8:9]
	v_mov_b64_e32 v[56:57], v[6:7]
	v_mov_b64_e32 v[54:55], v[4:5]
	v_mov_b64_e32 v[52:53], v[2:3]
	v_mov_b64_e32 v[50:51], v[0:1]
	v_mov_b64_e32 v[46:47], v[12:13]
	v_mov_b64_e32 v[44:45], v[10:11]
	v_mov_b64_e32 v[42:43], v[8:9]
	v_mov_b64_e32 v[40:41], v[6:7]
	v_mov_b64_e32 v[38:39], v[4:5]
	v_mov_b64_e32 v[36:37], v[2:3]
	v_mov_b64_e32 v[34:35], v[0:1]
	v_mov_b64_e32 v[30:31], v[12:13]
	v_mov_b64_e32 v[28:29], v[10:11]
	v_mov_b64_e32 v[26:27], v[8:9]
	v_mov_b64_e32 v[24:25], v[6:7]
	v_mov_b64_e32 v[22:23], v[4:5]
	v_mov_b64_e32 v[20:21], v[2:3]
	v_mov_b64_e32 v[18:19], v[0:1]
	v_mov_b64_e32 v[16:17], v[14:15]
	s_mov_b32 s16, 2
	s_mov_b32 s17, 0
	v_mov_b32_e32 v115, s28
	v_or_b32_e32 v132, 0x800, v130
	v_or_b32_e32 v134, 0x1000, v130
	v_or_b32_e32 v135, 0x1800, v130
	v_or_b32_e32 v136, 0x2000, v130
	v_or_b32_e32 v137, 0x2800, v130
	v_or_b32_e32 v138, 0x3000, v130
	v_or_b32_e32 v139, 0x3800, v130
	s_add_i32 s6, s6, 64
	v_mov_b32_e32 v148, 0xf149f2ca
	v_mov_b32_e32 v253, -1.0
	v_mov_b32_e32 v252, 0
	v_mov_b64_e32 v[236:237], 0
	v_mov_b64_e32 v[238:239], 0
	v_mov_b64_e32 v[240:241], 0
	v_mov_b64_e32 v[242:243], 0
	v_mov_b64_e32 v[244:245], 0
	v_mov_b64_e32 v[246:247], 0
	v_mov_b64_e32 v[248:249], 0
	v_mov_b64_e32 v[250:251], 0
	v_mov_b32_e32 v147, 0
	v_mov_b64_e32 v[14:15], v[12:13]
	v_mov_b64_e32 v[12:13], v[10:11]
	v_mov_b64_e32 v[10:11], v[8:9]
	v_mov_b64_e32 v[8:9], v[6:7]
	v_mov_b64_e32 v[6:7], v[4:5]
	v_mov_b64_e32 v[4:5], v[2:3]
	v_mov_b64_e32 v[2:3], v[0:1]
	s_mov_b32 s7, 0
	s_cmp_ge_u32 s7, s24
	s_cselect_b64 s[2:3], -1, 0
	s_and_b64 vcc, exec, s[2:3]
	s_cbranch_vccnz .LBB0_626
	s_branch .LBB0_625

; template <bool MASKED>
; __device__ __forceinline__ void softmax_tile(f32x16& s0, f32x16& s1, float& m, float& l, float& alpha, unsigned mlo, unsigned mhi, bf16x8 (&pk)[4]) {
;     ...
;     alpha = __builtin_amdgcn_exp2f(m - mn); m = mn;
;     float sum = 0.f;
; #pragma unroll
;     for (int r = 0; r < 16; ++r) {
;         float p0 = __builtin_amdgcn_exp2f(s0[r] - mn), p1 = __builtin_amdgcn_exp2f(s1[r] - mn);
;         if (MASKED) { if (s0[r] <= -1e29f) p0 = 0.f; if (s1[r] <= -1e29f) p1 = 0.f; }
;         s0[r] = p0; s1[r] = p1; sum += p0 + p1;
;     }
.LBB0_626:
	s_cmp_gt_i32 s7, s25
	s_cbranch_scc1 .LBB0_630
	s_mul_i32 s26, s17, 0xa000
	s_add_i32 s26, s26, 0
	v_add_u32_e32 v0, s26, v124
	v_add_u32_e32 v70, v0, v126
	v_add_u32_e32 v74, v0, v127
	ds_read_b128 v[66:69], v70
	ds_read_b128 v[70:73], v70 offset:8192
	ds_read_b128 v[150:153], v74
	ds_read_b128 v[154:157], v74 offset:8192
	v_add_u32_e32 v74, v0, v128
	v_add_u32_e32 v0, v0, v129
	ds_read_b128 v[158:161], v74
	ds_read_b128 v[162:165], v74 offset:8192
	ds_read_b128 v[166:169], v0
	ds_read_b128 v[170:173], v0 offset:8192
	s_waitcnt lgkmcnt(0)
	v_mfma_f32_32x32x16_bf16 v[82:97], v[66:69], v[98:101], v[236:251]
	v_mfma_f32_32x32x16_bf16 v[66:81], v[70:73], v[98:101], v[236:251]
	v_mfma_f32_32x32x16_bf16 v[82:97], v[150:153], v[102:105], v[82:97]
	v_mfma_f32_32x32x16_bf16 v[66:81], v[154:157], v[102:105], v[66:81]
	v_mfma_f32_32x32x16_bf16 v[82:97], v[158:161], v[106:109], v[82:97]
	v_mfma_f32_32x32x16_bf16 v[66:81], v[162:165], v[106:109], v[66:81]
	v_mfma_f32_32x32x16_bf16 v[82:97], v[166:169], v[110:113], v[82:97]
	v_mfma_f32_32x32x16_bf16 v[66:81], v[170:173], v[110:113], v[66:81]
	s_nop 11
	v_exp_f32_e32 v174, v82
	v_exp_f32_e32 v175, v83
	v_exp_f32_e32 v176, v84
	v_exp_f32_e32 v177, v85
	v_exp_f32_e32 v178, v86
	v_exp_f32_e32 v179, v87
	v_exp_f32_e32 v180, v88
	v_exp_f32_e32 v181, v89
	v_exp_f32_e32 v182, v90
	v_exp_f32_e32 v183, v91
	v_exp_f32_e32 v184, v92
	v_exp_f32_e32 v185, v93
	v_exp_f32_e32 v186, v94
	v_exp_f32_e32 v187, v95
	v_exp_f32_e32 v188, v96
	v_exp_f32_e32 v189, v97
	v_exp_f32_e32 v190, v66
	v_exp_f32_e32 v191, v67
	v_exp_f32_e32 v192, v68
	v_exp_f32_e32 v193, v69
	v_exp_f32_e32 v194, v70
	v_exp_f32_e32 v195, v71
	v_exp_f32_e32 v196, v72
	v_exp_f32_e32 v197, v73
	v_exp_f32_e32 v198, v74
	v_exp_f32_e32 v199, v75
	v_exp_f32_e32 v200, v76
	v_exp_f32_e32 v201, v77
	v_exp_f32_e32 v206, v78
	v_exp_f32_e32 v207, v79
	v_exp_f32_e32 v208, v80
	v_exp_f32_e32 v209, v81
	v_add_f32_e32 v150, v174, v176
	v_add_f32_e32 v151, v175, v177
	v_add_f32_e32 v152, v178, v180
	v_add_f32_e32 v153, v179, v181
	v_add_f32_e32 v154, v182, v184
	v_add_f32_e32 v155, v183, v185
	v_add_f32_e32 v156, v186, v188
	v_add_f32_e32 v157, v187, v189
	v_add_f32_e32 v158, v190, v192
	v_add_f32_e32 v159, v191, v193
	v_add_f32_e32 v160, v194, v196
	v_add_f32_e32 v161, v195, v197
	v_add_f32_e32 v162, v198, v200
	v_add_f32_e32 v163, v199, v201
	v_add_f32_e32 v164, v206, v208
	v_add_f32_e32 v165, v207, v209
	v_add_f32_e32 v150, v150, v152
	v_add_f32_e32 v151, v151, v153
	v_add_f32_e32 v154, v154, v156
	v_add_f32_e32 v155, v155, v157
	v_add_f32_e32 v158, v158, v160
	v_add_f32_e32 v159, v159, v161
	v_add_f32_e32 v162, v162, v164
	v_add_f32_e32 v163, v163, v165
	v_add_f32_e32 v150, v150, v154
	v_add_f32_e32 v151, v151, v155
	v_add_f32_e32 v158, v158, v162
	v_add_f32_e32 v159, v159, v163
	v_add_f32_e32 v150, v150, v158
	v_add_f32_e32 v151, v151, v159
	v_add_f32_e32 v164, v150, v151
	v_mov_b32_e32 v0, 1.0
	v_mov_b32_e32 v146, v148
	v_cmp_lt_f32_e32 vcc, v253, v164
	s_cbranch_vccz .Lm2_cfast
; __device__ __forceinline__ unsigned cvtpk(float lo, float hi) { unsigned r; asm("v_cvt_pk_bf16_f32 %0, %1, %2" : "=v"(r) : "v"(lo), "v"(hi)); return r; }
; __device__ __forceinline__ float max_x32(float v) { const unsigned u = __float_as_uint(v); auto r = __builtin_amdgcn_permlane32_swap(u, u, false, false); return fmaxf(__uint_as_float(r[0]), __uint_as_float(r[1])); }
; template <bool MASKED>
; __device__ __forceinline__ void softmax_tile(f32x16& s0, f32x16& s1, float& m, float& l, float& alpha, unsigned mlo, unsigned mhi, bf16x8 (&pk)[4]) {
;     ...
;     if (MASKED) {
; #pragma unroll
;         for (int r = 0; r < 16; ++r) { const int bit = (r & 3) + 8 * (r >> 2); if (!((mlo >> bit) & 1u)) s0[r] = NEG; if (!((mhi >> bit) & 1u)) s1[r] = NEG; }
;     }
;     float mx = fmaxf(s0[0], s1[0]);
; #pragma unroll
;     for (int r = 1; r < 16; ++r) mx = fmaxf(mx, fmaxf(s0[r], s1[r]));
;     mx = max_x32(mx);
;     const float mn = fmaxf(m, mx);
;     alpha = __builtin_amdgcn_exp2f(m - mn); m = mn;
;     float sum = 0.f;
; #pragma unroll
;     for (int r = 0; r < 16; ++r) {
;         float p0 = __builtin_amdgcn_exp2f(s0[r] - mn), p1 = __builtin_amdgcn_exp2f(s1[r] - mn);
;         if (MASKED) { if (s0[r] <= -1e29f) p0 = 0.f; if (s1[r] <= -1e29f) p1 = 0.f; }
;         s0[r] = p0; s1[r] = p1; sum += p0 + p1;
;     }
;     l = l * alpha + sum;
; #pragma unroll
;     for (int k2 = 0; k2 < 2; ++k2) {
;         u32x4 a, b;
;         a.x = cvtpk(s0[8 * k2 + 0], s0[8 * k2 + 1]); a.y = cvtpk(s0[8 * k2 + 2], s0[8 * k2 + 3]); a.z = cvtpk(s0[8 * k2 + 4], s0[8 * k2 + 5]); a.w = cvtpk(s0[8 * k2 + 6], s0[8 * k2 + 7]);
;         b.x = cvtpk(s1[8 * k2 + 0], s1[8 * k2 + 1]); b.y = cvtpk(s1[8 * k2 + 2], s1[8 * k2 + 3]); b.z = cvtpk(s1[8 * k2 + 4], s1[8 * k2 + 5]); b.w = cvtpk(s1[8 * k2 + 6], s1[8 * k2 + 7]);
;         pk[k2] = __builtin_bit_cast(bf16x8, a); pk[2 + k2] = __builtin_bit_cast(bf16x8, b);
;     }
	v_max3_f32 v150, v82, v83, v84
	v_max3_f32 v151, v85, v86, v87
	v_max3_f32 v152, v88, v89, v90
	v_max3_f32 v153, v91, v92, v93
	v_max3_f32 v154, v94, v95, v96
	v_max3_f32 v155, v97, v66, v67
	v_max3_f32 v156, v68, v69, v70
	v_max3_f32 v157, v71, v72, v73
	v_max3_f32 v158, v74, v75, v76
	v_max3_f32 v159, v77, v78, v79
	v_max3_f32 v150, v150, v151, v152
	v_max3_f32 v153, v153, v154, v155
	v_max3_f32 v156, v156, v157, v158
	v_max3_f32 v159, v159, v80, v81
	v_max3_f32 v150, v150, v153, v156
	v_max_f32_e32 v150, v150, v159
	v_mov_b32_e32 v151, v150
	s_nop 1
	v_permlane32_swap_b32_e32 v150, v151
	v_max_f32_e32 v150, v150, v151
	v_mov_b32_e32 v151, 0x41000000
	v_mov_b32_e32 v152, s97
	v_cmp_gt_f32_e32 vcc, 0, v253
	s_nop 1
	v_cndmask_b32_e32 v151, v151, v152, vcc
	v_cmp_lt_f32_e32 vcc, v151, v150
	s_nop 1
	v_add_f32_e32 v151, v150, v252
	v_cndmask_b32_e32 v146, v148, v151, vcc
	v_sub_f32_e32 v151, v146, v252
	v_cndmask_b32_e32 v151, 0, v151, vcc
	v_mov_b32_e32 v150, 0x46800000
	v_cndmask_b32_e32 v253, v253, v150, vcc
	v_cndmask_b32_e32 v252, v252, v146, vcc
	v_sub_f32_e32 v0, v148, v146
	v_exp_f32_e32 v0, v0
	v_sub_f32_e32 v82, v82, v151
	v_sub_f32_e32 v83, v83, v151
	v_sub_f32_e32 v84, v84, v151
	v_sub_f32_e32 v85, v85, v151
	v_sub_f32_e32 v86, v86, v151
	v_sub_f32_e32 v87, v87, v151
	v_sub_f32_e32 v88, v88, v151
	v_sub_f32_e32 v89, v89, v151
	v_sub_f32_e32 v90, v90, v151
	v_sub_f32_e32 v91, v91, v151
	v_sub_f32_e32 v92, v92, v151
	v_sub_f32_e32 v93, v93, v151
	v_sub_f32_e32 v94, v94, v151
	v_sub_f32_e32 v95, v95, v151
	v_sub_f32_e32 v96, v96, v151
	v_sub_f32_e32 v97, v97, v151
	v_sub_f32_e32 v66, v66, v151
	v_sub_f32_e32 v67, v67, v151
	v_sub_f32_e32 v68, v68, v151
	v_sub_f32_e32 v69, v69, v151
	v_sub_f32_e32 v70, v70, v151
	v_sub_f32_e32 v71, v71, v151
	v_sub_f32_e32 v72, v72, v151
	v_sub_f32_e32 v73, v73, v151
	v_sub_f32_e32 v74, v74, v151
	v_sub_f32_e32 v75, v75, v151
	v_sub_f32_e32 v76, v76, v151
	v_sub_f32_e32 v77, v77, v151
	v_sub_f32_e32 v78, v78, v151
	v_sub_f32_e32 v79, v79, v151
	v_sub_f32_e32 v80, v80, v151
	v_sub_f32_e32 v81, v81, v151
	v_sub_f32_e32 v236, 0, v252
	v_sub_f32_e32 v237, 0, v252
	v_sub_f32_e32 v238, 0, v252
	v_sub_f32_e32 v239, 0, v252
	v_sub_f32_e32 v240, 0, v252
	v_sub_f32_e32 v241, 0, v252
	v_sub_f32_e32 v242, 0, v252
	v_sub_f32_e32 v243, 0, v252
	v_sub_f32_e32 v244, 0, v252
	v_sub_f32_e32 v245, 0, v252
	v_sub_f32_e32 v246, 0, v252
	v_sub_f32_e32 v247, 0, v252
	v_sub_f32_e32 v248, 0, v252
	v_sub_f32_e32 v249, 0, v252
	v_sub_f32_e32 v250, 0, v252
	v_sub_f32_e32 v251, 0, v252
	v_exp_f32_e32 v174, v82
	v_exp_f32_e32 v175, v83
	v_exp_f32_e32 v176, v84
	v_exp_f32_e32 v177, v85
	v_exp_f32_e32 v178, v86
	v_exp_f32_e32 v179, v87
	v_exp_f32_e32 v180, v88
	v_exp_f32_e32 v181, v89
	v_exp_f32_e32 v182, v90
	v_exp_f32_e32 v183, v91
	v_exp_f32_e32 v184, v92
	v_exp_f32_e32 v185, v93
	v_exp_f32_e32 v186, v94
	v_exp_f32_e32 v187, v95
	v_exp_f32_e32 v188, v96
	v_exp_f32_e32 v189, v97
	v_exp_f32_e32 v190, v66
	v_exp_f32_e32 v191, v67
	v_exp_f32_e32 v192, v68
	v_exp_f32_e32 v193, v69
	v_exp_f32_e32 v194, v70
	v_exp_f32_e32 v195, v71
	v_exp_f32_e32 v196, v72
	v_exp_f32_e32 v197, v73
	v_exp_f32_e32 v198, v74
	v_exp_f32_e32 v199, v75
	v_exp_f32_e32 v200, v76
	v_exp_f32_e32 v201, v77
	v_exp_f32_e32 v206, v78
	v_exp_f32_e32 v207, v79
	v_exp_f32_e32 v208, v80
	v_exp_f32_e32 v209, v81
	v_add_f32_e32 v150, v174, v176
	v_add_f32_e32 v151, v175, v177
	v_add_f32_e32 v152, v178, v180
	v_add_f32_e32 v153, v179, v181
	v_add_f32_e32 v154, v182, v184
	v_add_f32_e32 v155, v183, v185
	v_add_f32_e32 v156, v186, v188
	v_add_f32_e32 v157, v187, v189
	v_add_f32_e32 v158, v190, v192
	v_add_f32_e32 v159, v191, v193
	v_add_f32_e32 v160, v194, v196
	v_add_f32_e32 v161, v195, v197
	v_add_f32_e32 v162, v198, v200
	v_add_f32_e32 v163, v199, v201
	v_add_f32_e32 v164, v206, v208
	v_add_f32_e32 v165, v207, v209
	v_add_f32_e32 v150, v150, v152
	v_add_f32_e32 v151, v151, v153
	v_add_f32_e32 v154, v154, v156
	v_add_f32_e32 v155, v155, v157
	v_add_f32_e32 v158, v158, v160
	v_add_f32_e32 v159, v159, v161
	v_add_f32_e32 v162, v162, v164
	v_add_f32_e32 v163, v163, v165
	v_add_f32_e32 v150, v150, v154
	v_add_f32_e32 v151, v151, v155
	v_add_f32_e32 v158, v158, v162
	v_add_f32_e32 v159, v159, v163
	v_add_f32_e32 v150, v150, v158
	v_add_f32_e32 v151, v151, v159
	v_add_f32_e32 v164, v150, v151
.Lm2_cfast:
	v_cvt_pk_bf16_f32 v66, v190, v191
	v_cvt_pk_bf16_f32 v67, v192, v193
	v_cvt_pk_bf16_f32 v68, v194, v195
	v_cvt_pk_bf16_f32 v69, v196, v197
	v_cvt_pk_bf16_f32 v70, v198, v199
	v_cvt_pk_bf16_f32 v71, v200, v201
	v_cvt_pk_bf16_f32 v72, v206, v207
	v_cvt_pk_bf16_f32 v73, v208, v209
	v_cvt_pk_bf16_f32 v74, v174, v175
	v_cvt_pk_bf16_f32 v75, v176, v177
	v_cvt_pk_bf16_f32 v76, v178, v179
	v_cvt_pk_bf16_f32 v77, v180, v181
	v_cvt_pk_bf16_f32 v78, v182, v183
	v_cvt_pk_bf16_f32 v79, v184, v185
	v_cvt_pk_bf16_f32 v80, v186, v187
	v_cvt_pk_bf16_f32 v81, v188, v189
	v_fmac_f32_e32 v164, v147, v0
	v_cmp_neq_f32_e32 vcc, 1.0, v0
	s_cbranch_vccz .LBB0_629
	v_mul_f32_e32 v64, v64, v0
	v_mul_f32_e32 v65, v65, v0
	v_mul_f32_e32 v62, v62, v0
	v_mul_f32_e32 v63, v63, v0
	v_mul_f32_e32 v60, v60, v0
	v_mul_f32_e32 v61, v61, v0
	v_mul_f32_e32 v58, v58, v0
	v_mul_f32_e32 v59, v59, v0
	v_mul_f32_e32 v56, v56, v0
	v_mul_f32_e32 v57, v57, v0
	v_mul_f32_e32 v54, v54, v0
	v_mul_f32_e32 v55, v55, v0
	v_mul_f32_e32 v52, v52, v0
	v_mul_f32_e32 v53, v53, v0
	v_mul_f32_e32 v50, v50, v0
	v_mul_f32_e32 v51, v51, v0
	v_mul_f32_e32 v48, v48, v0
	v_mul_f32_e32 v49, v49, v0
	v_mul_f32_e32 v46, v46, v0
	v_mul_f32_e32 v47, v47, v0
	v_mul_f32_e32 v44, v44, v0
	v_mul_f32_e32 v45, v45, v0
	v_mul_f32_e32 v42, v42, v0
	v_mul_f32_e32 v43, v43, v0
	v_mul_f32_e32 v40, v40, v0
	v_mul_f32_e32 v41, v41, v0
	v_mul_f32_e32 v38, v38, v0
	v_mul_f32_e32 v39, v39, v0
	v_mul_f32_e32 v36, v36, v0
	v_mul_f32_e32 v37, v37, v0
	v_mul_f32_e32 v34, v34, v0
	v_mul_f32_e32 v35, v35, v0
	v_mul_f32_e32 v32, v32, v0
	v_mul_f32_e32 v33, v33, v0
	v_mul_f32_e32 v30, v30, v0
	v_mul_f32_e32 v31, v31, v0
	v_mul_f32_e32 v28, v28, v0
	v_mul_f32_e32 v29, v29, v0
	v_mul_f32_e32 v26, v26, v0
	v_mul_f32_e32 v27, v27, v0
	v_mul_f32_e32 v24, v24, v0
	v_mul_f32_e32 v25, v25, v0
	v_mul_f32_e32 v22, v22, v0
	v_mul_f32_e32 v23, v23, v0
	v_mul_f32_e32 v20, v20, v0
	v_mul_f32_e32 v21, v21, v0
	v_mul_f32_e32 v18, v18, v0
	v_mul_f32_e32 v19, v19, v0
	v_mul_f32_e32 v16, v16, v0
	v_mul_f32_e32 v17, v17, v0
	v_mul_f32_e32 v14, v14, v0
	v_mul_f32_e32 v15, v15, v0
	v_mul_f32_e32 v12, v12, v0
	v_mul_f32_e32 v13, v13, v0
	v_mul_f32_e32 v10, v10, v0
	v_mul_f32_e32 v11, v11, v0
	v_mul_f32_e32 v8, v8, v0
	v_mul_f32_e32 v9, v9, v0
	v_mul_f32_e32 v6, v6, v0
	v_mul_f32_e32 v7, v7, v0
	v_mul_f32_e32 v4, v4, v0
	v_mul_f32_e32 v5, v5, v0
	v_mul_f32_e32 v2, v2, v0
	v_mul_f32_e32 v3, v3, v0
